# v24 + cross-half row-max exchange via v_permlane32_swap instead of ds_bpermute in the prompt tile bodies
# baseline (speedup 1.0000x reference)
.LBB0_803:
	s_cmp_gt_u32 s74, s30
	s_cselect_b64 s[18:19], -1, 0
	s_and_b64 vcc, s[18:19], exec
	s_mul_i32 s18, s64, 0x2400
	s_cselect_b32 s20, s67, 0
	s_add_i32 s21, s18, 0
	s_mov_b64 s[18:19], -1
	v_add3_u32 v99, s21, v103, v104
	v_lshl_add_u32 v0, s20, 10, v107
	s_cbranch_vccnz .LBB0_805
	ds_read_b128 v[34:37], v99
	ds_read_b128 v[38:41], v99 offset:32
	v_mov_b32_e32 v111, v0
	s_mov_b64 s[18:19], 0
	s_waitcnt lgkmcnt(1)
	v_mfma_f32_32x32x16_bf16 v[50:65], v[34:37], v[66:69], 0
	ds_read_b128 v[34:37], v99 offset:64
	ds_read_b128 v[124:127], v99 offset:96
	ds_read_b128 v[42:45], v99 offset:4608
	ds_read_b128 v[128:131], v99 offset:4640
	ds_read_b128 v[132:135], v99 offset:4672
	ds_read_b128 v[136:139], v99 offset:4704
	s_nop 0
	v_add_u32_e32 v123, -16, v111
	v_cvt_f32_u32_e32 v100, v111
	v_cvt_f32_u32_e32 v101, v123
	s_waitcnt lgkmcnt(6)
	v_mfma_f32_32x32x16_bf16 v[50:65], v[38:41], v[70:73], v[50:65]
	v_and_b32_e32 v39, 64, v228
	v_subrev_u32_e32 v183, 48, v111
	v_subrev_u32_e32 v188, 32, v111
	v_xor_b32_e32 v38, 32, v228
	v_add_u32_e32 v39, 64, v39
	v_cvt_f32_u32_e32 v113, v183
	v_cvt_f32_u32_e32 v112, v188
	s_waitcnt lgkmcnt(5)
	v_mfma_f32_32x32x16_bf16 v[50:65], v[34:37], v[74:77], v[50:65]
	v_cmp_lt_i32_e32 vcc, v38, v39
	v_add_u32_e32 v189, 0xffffffb0, v111
	v_subrev_u32_e32 v190, 64, v111
	v_cndmask_b32_e32 v34, v228, v38, vcc
	v_cmp_gt_u32_e32 vcc, s88, v123
	v_lshlrev_b32_e32 v184, 2, v34
	v_cvt_f32_u32_e32 v187, v189
	s_waitcnt lgkmcnt(4)
	v_mfma_f32_32x32x16_bf16 v[50:65], v[124:127], v[78:81], v[50:65]
	v_cvt_f32_u32_e32 v186, v190
	v_add_u32_e32 v123, 0xffffffa0, v111
	v_add_u32_e32 v125, 0xffffff00, v111
	s_waitcnt lgkmcnt(3)
	v_mfma_f32_32x32x16_bf16 v[34:49], v[42:45], v[66:69], 0
	s_nop 6
	v_fma_f32 v50, -v118, v100, v50
	v_fma_f32 v51, -v119, v101, v51
	v_fma_f32 v52, -v118, v112, v52
	v_fma_f32 v53, -v119, v113, v53
	v_cndmask_b32_e32 v100, v144, v51, vcc
	v_cmp_gt_u32_e32 vcc, s88, v111
	v_pk_fma_f32 v[54:55], v[118:119], v[186:187], v[54:55] neg_lo:[1,0,0] neg_hi:[1,0,0]
	s_nop 0
	v_cndmask_b32_e32 v101, v144, v50, vcc
	v_cmp_gt_u32_e32 vcc, s88, v183
	v_max3_f32 v50, v101, s28, v100
	s_waitcnt lgkmcnt(2)
	v_mfma_f32_32x32x16_bf16 v[34:49], v[128:131], v[70:73], v[34:49]
	v_cndmask_b32_e32 v112, v144, v53, vcc
	v_cmp_gt_u32_e32 vcc, s88, v188
	v_add_u32_e32 v53, 0xffffff90, v111
	v_cvt_f32_u32_e32 v51, v53
	v_cndmask_b32_e32 v113, v144, v52, vcc
	v_max3_f32 v52, v50, v113, v112
	v_cvt_f32_u32_e32 v50, v123
	v_cmp_gt_u32_e32 vcc, s88, v189
	s_waitcnt lgkmcnt(1)
	v_mfma_f32_32x32x16_bf16 v[34:49], v[132:135], v[74:77], v[34:49]
	v_fma_f32 v50, -v118, v50, v56
	v_fma_f32 v51, -v119, v51, v57
	v_cndmask_b32_e32 v55, v144, v55, vcc
	v_cmp_gt_u32_e32 vcc, s88, v190
	v_add_u32_e32 v57, 0xfffffef0, v111
	s_nop 0
	v_cndmask_b32_e32 v54, v144, v54, vcc
	v_max3_f32 v124, v52, v54, v55
	v_cmp_gt_u32_e32 vcc, s88, v53
	v_cvt_f32_u32_e32 v53, v57
	v_cvt_f32_u32_e32 v52, v125
	v_cndmask_b32_e32 v56, v144, v51, vcc
	v_cmp_gt_u32_e32 vcc, s88, v123
	s_waitcnt lgkmcnt(0)
	v_mfma_f32_32x32x16_bf16 v[34:49], v[136:139], v[78:81], v[34:49]
	v_cndmask_b32_e32 v123, v144, v50, vcc
	v_fma_f32 v50, -v118, v52, v58
	v_fma_f32 v51, -v119, v53, v59
	v_add_u32_e32 v58, 0xfffffed0, v111
	v_add_u32_e32 v59, 0xfffffee0, v111
	v_cvt_f32_u32_e32 v53, v58
	v_cvt_f32_u32_e32 v52, v59
	v_cmp_gt_u32_e32 vcc, s88, v57
	v_max3_f32 v124, v124, v123, v56
	s_nop 0
	v_cndmask_b32_e32 v57, v144, v51, vcc
	v_cmp_gt_u32_e32 vcc, s88, v125
	s_nop 1
	v_cndmask_b32_e32 v125, v144, v50, vcc
	v_pk_fma_f32 v[50:51], v[118:119], v[52:53], v[60:61] neg_lo:[1,0,0] neg_hi:[1,0,0]
	v_add_u32_e32 v60, 0xfffffeb0, v111
	v_add_u32_e32 v61, 0xfffffec0, v111
	v_cvt_f32_u32_e32 v53, v60
	v_cvt_f32_u32_e32 v52, v61
	v_cmp_gt_u32_e32 vcc, s88, v58
	v_max3_f32 v124, v124, v125, v57
	s_nop 0
	v_cndmask_b32_e32 v58, v144, v51, vcc
	v_cmp_gt_u32_e32 vcc, s88, v59
	s_nop 1
	v_cndmask_b32_e32 v59, v144, v50, vcc
	v_pk_fma_f32 v[50:51], v[118:119], v[52:53], v[62:63] neg_lo:[1,0,0] neg_hi:[1,0,0]
	v_add_u32_e32 v62, 0xfffffe90, v111
	v_add_u32_e32 v63, 0xfffffea0, v111
	v_cvt_f32_u32_e32 v53, v62
	v_cvt_f32_u32_e32 v52, v63
	v_cmp_gt_u32_e32 vcc, s88, v60
	v_max3_f32 v124, v124, v59, v58
	s_nop 0
	v_cndmask_b32_e32 v60, v144, v51, vcc
	v_cmp_gt_u32_e32 vcc, s88, v61
	s_nop 1
	v_cndmask_b32_e32 v61, v144, v50, vcc
	v_pk_fma_f32 v[50:51], v[118:119], v[52:53], v[64:65] neg_lo:[1,0,0] neg_hi:[1,0,0]
	v_cmp_gt_u32_e32 vcc, s88, v62
	v_add_u32_e32 v64, 0xfffffe00, v111
	v_cvt_f32_u32_e32 v52, v64
	v_cndmask_b32_e32 v62, v144, v51, vcc
	v_add_u32_e32 v51, 0xfffffdf0, v111
	v_cvt_f32_u32_e32 v53, v51
	v_cmp_gt_u32_e32 vcc, s88, v63
	v_max3_f32 v124, v124, v61, v60
	v_pk_fma_f32 v[34:35], v[118:119], v[52:53], v[34:35] neg_lo:[1,0,0] neg_hi:[1,0,0]
	v_cndmask_b32_e32 v63, v144, v50, vcc
	v_max3_f32 v65, v124, v63, v62
	v_add_u32_e32 v53, 0xfffffdd0, v111
	v_add_u32_e32 v124, 0xfffffde0, v111
	v_cmp_gt_u32_e32 vcc, s88, v51
	v_cvt_f32_u32_e32 v51, v53
	v_cvt_f32_u32_e32 v50, v124
	v_cndmask_b32_e32 v52, v144, v35, vcc
	v_cmp_gt_u32_e32 vcc, s88, v64
	s_nop 1
	v_cndmask_b32_e32 v64, v144, v34, vcc
	v_pk_fma_f32 v[34:35], v[118:119], v[50:51], v[36:37] neg_lo:[1,0,0] neg_hi:[1,0,0]
	v_cmp_gt_u32_e32 vcc, s88, v53
	v_add_u32_e32 v51, 0xfffffdb0, v111
	v_add_u32_e32 v53, 0xfffffdc0, v111
	v_cvt_f32_u32_e32 v37, v51
	v_cvt_f32_u32_e32 v36, v53
	v_cndmask_b32_e32 v50, v144, v35, vcc
	v_cmp_gt_u32_e32 vcc, s88, v124
	v_max3_f32 v65, v65, v64, v52
	s_nop 0
	v_cndmask_b32_e32 v124, v144, v34, vcc
	v_pk_fma_f32 v[34:35], v[118:119], v[36:37], v[38:39] neg_lo:[1,0,0] neg_hi:[1,0,0]
	v_cmp_gt_u32_e32 vcc, s88, v51
	v_add_u32_e32 v39, 0xfffffd90, v111
	v_add_u32_e32 v51, 0xfffffda0, v111
	v_cvt_f32_u32_e32 v37, v39
	v_cvt_f32_u32_e32 v36, v51
	v_cndmask_b32_e32 v38, v144, v35, vcc
	v_cmp_gt_u32_e32 vcc, s88, v53
	v_max3_f32 v65, v65, v124, v50
	s_nop 0
	v_cndmask_b32_e32 v53, v144, v34, vcc
	v_pk_fma_f32 v[34:35], v[118:119], v[36:37], v[40:41] neg_lo:[1,0,0] neg_hi:[1,0,0]
	v_add_u32_e32 v40, 0xfffffcf0, v111
	v_add_u32_e32 v41, 0xfffffd00, v111
	v_cvt_f32_u32_e32 v37, v40
	v_cvt_f32_u32_e32 v36, v41
	v_cmp_gt_u32_e32 vcc, s88, v39
	v_max3_f32 v65, v65, v53, v38
	s_nop 0
	v_cndmask_b32_e32 v39, v144, v35, vcc
	v_cmp_gt_u32_e32 vcc, s88, v51
	s_nop 1
	v_cndmask_b32_e32 v51, v144, v34, vcc
	v_pk_fma_f32 v[34:35], v[118:119], v[36:37], v[42:43] neg_lo:[1,0,0] neg_hi:[1,0,0]
	v_add_u32_e32 v42, 0xfffffcd0, v111
	v_add_u32_e32 v43, 0xfffffce0, v111
	v_cvt_f32_u32_e32 v37, v42
	v_cvt_f32_u32_e32 v36, v43
	v_cmp_gt_u32_e32 vcc, s88, v40
	v_max3_f32 v65, v65, v51, v39
	s_nop 0
	v_cndmask_b32_e32 v40, v144, v35, vcc
	v_cmp_gt_u32_e32 vcc, s88, v41
	s_nop 1
	v_cndmask_b32_e32 v41, v144, v34, vcc
	v_pk_fma_f32 v[34:35], v[118:119], v[36:37], v[44:45] neg_lo:[1,0,0] neg_hi:[1,0,0]
	v_add_u32_e32 v44, 0xfffffcb0, v111
	v_add_u32_e32 v45, 0xfffffcc0, v111
	v_cvt_f32_u32_e32 v37, v44
	v_cvt_f32_u32_e32 v36, v45
	v_cmp_gt_u32_e32 vcc, s88, v42
	v_max3_f32 v65, v65, v41, v40
	s_nop 0
	v_cndmask_b32_e32 v42, v144, v35, vcc
	v_cmp_gt_u32_e32 vcc, s88, v43
	s_nop 1
	v_cndmask_b32_e32 v43, v144, v34, vcc
	v_pk_fma_f32 v[34:35], v[118:119], v[36:37], v[46:47] neg_lo:[1,0,0] neg_hi:[1,0,0]
	v_add_u32_e32 v46, 0xfffffc90, v111
	v_add_u32_e32 v47, 0xfffffca0, v111
	v_cvt_f32_u32_e32 v37, v46
	v_cvt_f32_u32_e32 v36, v47
	v_cmp_gt_u32_e32 vcc, s88, v44
	v_max3_f32 v65, v65, v43, v42
	s_nop 0
	v_cndmask_b32_e32 v44, v144, v35, vcc
	v_cmp_gt_u32_e32 vcc, s88, v45
	s_nop 1
	v_cndmask_b32_e32 v45, v144, v34, vcc
	v_pk_fma_f32 v[34:35], v[118:119], v[36:37], v[48:49] neg_lo:[1,0,0] neg_hi:[1,0,0]
	v_cmp_gt_u32_e32 vcc, s88, v46
	v_max3_f32 v65, v65, v45, v44
	s_nop 0
	v_cndmask_b32_e32 v35, v144, v35, vcc
	v_cmp_gt_u32_e32 vcc, s88, v47
	s_nop 1
	v_cndmask_b32_e32 v36, v144, v34, vcc
	v_max3_f32 v34, v65, v36, v35
	v_mov_b32_e32 v37, v34
	s_nop 1
	v_permlane32_swap_b32 v37, v34
	s_waitcnt lgkmcnt(0)
	v_max3_f32 v34, v109, v34, v37
	v_sub_f32_e32 v37, v109, v34
	v_exp_f32_e32 v37, v37
	v_sub_f32_e32 v46, v101, v34
	v_exp_f32_e32 v46, v46
	v_cmp_gt_f32_e32 vcc, v34, v109
	v_sub_f32_e32 v47, v100, v34
	s_cmp_eq_u64 vcc, 0
	v_exp_f32_e32 v47, v47
	v_mul_f32_e32 v37, v110, v37
	s_cselect_b64 vcc, -1, 0
	v_cndmask_b32_e32 v37, v37, v110, vcc
	v_add_f32_e32 v46, 0, v46
	v_cmp_lt_f32_e32 vcc, s29, v101
	v_sub_f32_e32 v48, v112, v34
	v_exp_f32_e32 v48, v48
	v_cndmask_b32_e32 v46, 0, v46, vcc
	v_cmp_lt_f32_e32 vcc, s29, v100
	s_nop 1
	v_cndmask_b32_e32 v47, 0, v47, vcc
	v_add_f32_e32 v46, v47, v46
	v_sub_f32_e32 v47, v113, v34
	v_exp_f32_e32 v47, v47
	v_cmp_lt_f32_e32 vcc, s29, v113
	s_nop 1
	v_cndmask_b32_e32 v47, 0, v47, vcc
	v_cmp_lt_f32_e32 vcc, s29, v112
	v_add_f32_e32 v46, v47, v46
	s_nop 0
	v_cndmask_b32_e32 v47, 0, v48, vcc
	v_add_f32_e32 v46, v47, v46
	v_sub_f32_e32 v47, v54, v34
	v_exp_f32_e32 v47, v47
	v_sub_f32_e32 v48, v55, v34
	v_exp_f32_e32 v48, v48
	v_cmp_lt_f32_e32 vcc, s29, v54
	s_nop 1
	v_cndmask_b32_e32 v47, 0, v47, vcc
	v_cmp_lt_f32_e32 vcc, s29, v55
	v_add_f32_e32 v46, v47, v46
	s_nop 0
	v_cndmask_b32_e32 v47, 0, v48, vcc
	v_add_f32_e32 v46, v47, v46
	v_sub_f32_e32 v47, v123, v34
	v_exp_f32_e32 v47, v47
	v_sub_f32_e32 v48, v56, v34
	v_exp_f32_e32 v48, v48
	v_cmp_lt_f32_e32 vcc, s29, v123
	s_nop 1
	v_cndmask_b32_e32 v47, 0, v47, vcc
	v_cmp_lt_f32_e32 vcc, s29, v56
	v_add_f32_e32 v46, v47, v46
	s_nop 0
	v_cndmask_b32_e32 v47, 0, v48, vcc
	v_add_f32_e32 v46, v47, v46
	v_sub_f32_e32 v47, v125, v34
	v_exp_f32_e32 v47, v47
	v_sub_f32_e32 v48, v57, v34
	v_exp_f32_e32 v48, v48
	v_cmp_lt_f32_e32 vcc, s29, v125
	s_nop 1
	v_cndmask_b32_e32 v47, 0, v47, vcc
	v_cmp_lt_f32_e32 vcc, s29, v57
	v_add_f32_e32 v46, v47, v46
	s_nop 0
	v_cndmask_b32_e32 v47, 0, v48, vcc
	v_add_f32_e32 v46, v47, v46
	v_sub_f32_e32 v47, v59, v34
	v_exp_f32_e32 v47, v47
	v_sub_f32_e32 v48, v58, v34
	v_exp_f32_e32 v48, v48
	v_cmp_lt_f32_e32 vcc, s29, v59
	s_nop 1
	v_cndmask_b32_e32 v47, 0, v47, vcc
	v_cmp_lt_f32_e32 vcc, s29, v58
	v_add_f32_e32 v46, v47, v46
	s_nop 0
	v_cndmask_b32_e32 v47, 0, v48, vcc
	v_add_f32_e32 v46, v47, v46
	v_sub_f32_e32 v47, v61, v34
	v_exp_f32_e32 v47, v47
	v_sub_f32_e32 v48, v60, v34
	v_exp_f32_e32 v48, v48
	v_cmp_lt_f32_e32 vcc, s29, v61
	s_nop 1
	v_cndmask_b32_e32 v47, 0, v47, vcc
	v_cmp_lt_f32_e32 vcc, s29, v60
	v_add_f32_e32 v46, v47, v46
	s_nop 0
	v_cndmask_b32_e32 v47, 0, v48, vcc
	v_add_f32_e32 v46, v47, v46
	v_sub_f32_e32 v47, v63, v34
	v_exp_f32_e32 v47, v47
	v_sub_f32_e32 v48, v62, v34
	v_exp_f32_e32 v48, v48
	v_cmp_lt_f32_e32 vcc, s29, v63
	s_nop 1
	v_cndmask_b32_e32 v47, 0, v47, vcc
	v_cmp_lt_f32_e32 vcc, s29, v62
	v_add_f32_e32 v46, v47, v46
	s_nop 0
	v_cndmask_b32_e32 v47, 0, v48, vcc
	v_add_f32_e32 v46, v47, v46
	v_sub_f32_e32 v47, v64, v34
	v_exp_f32_e32 v47, v47
	v_sub_f32_e32 v48, v52, v34
	v_exp_f32_e32 v48, v48
	v_cmp_lt_f32_e32 vcc, s29, v64
	s_nop 1
	v_cndmask_b32_e32 v47, 0, v47, vcc
	v_cmp_lt_f32_e32 vcc, s29, v52
	v_add_f32_e32 v46, v47, v46
	s_nop 0
	v_cndmask_b32_e32 v47, 0, v48, vcc
	v_add_f32_e32 v46, v47, v46
	v_sub_f32_e32 v47, v124, v34
	v_exp_f32_e32 v47, v47
	v_sub_f32_e32 v48, v50, v34
	v_exp_f32_e32 v48, v48
	v_cmp_lt_f32_e32 vcc, s29, v124
	s_nop 1
	v_cndmask_b32_e32 v47, 0, v47, vcc
	v_cmp_lt_f32_e32 vcc, s29, v50
	v_add_f32_e32 v46, v47, v46
	s_nop 0
	v_cndmask_b32_e32 v47, 0, v48, vcc
	v_add_f32_e32 v46, v47, v46
	v_sub_f32_e32 v47, v53, v34
	v_exp_f32_e32 v47, v47
	v_sub_f32_e32 v48, v38, v34
	v_exp_f32_e32 v48, v48
	v_cmp_lt_f32_e32 vcc, s29, v53
	s_nop 1
	v_cndmask_b32_e32 v47, 0, v47, vcc
	v_cmp_lt_f32_e32 vcc, s29, v38
	v_add_f32_e32 v46, v47, v46
	v_sub_f32_e32 v47, v39, v34
	v_cndmask_b32_e32 v38, 0, v48, vcc
	v_add_f32_e32 v38, v38, v46
	v_sub_f32_e32 v46, v51, v34
	v_exp_f32_e32 v46, v46
	v_exp_f32_e32 v47, v47
	v_cmp_lt_f32_e32 vcc, s29, v51
	s_nop 1
	v_cndmask_b32_e32 v46, 0, v46, vcc
	v_cmp_lt_f32_e32 vcc, s29, v39
	v_add_f32_e32 v38, v46, v38
	v_sub_f32_e32 v46, v40, v34
	v_cndmask_b32_e32 v39, 0, v47, vcc
	v_add_f32_e32 v38, v39, v38
	v_sub_f32_e32 v39, v41, v34
	v_exp_f32_e32 v39, v39
	v_exp_f32_e32 v46, v46
	v_cmp_lt_f32_e32 vcc, s29, v41
	s_nop 1
	v_cndmask_b32_e32 v39, 0, v39, vcc
	v_cmp_lt_f32_e32 vcc, s29, v40
	v_add_f32_e32 v38, v39, v38
	v_sub_f32_e32 v40, v42, v34
	v_cndmask_b32_e32 v39, 0, v46, vcc
	v_add_f32_e32 v38, v39, v38
	v_sub_f32_e32 v39, v43, v34
	v_exp_f32_e32 v39, v39
	v_exp_f32_e32 v40, v40
	v_cmp_lt_f32_e32 vcc, s29, v43
	s_nop 1
	v_cndmask_b32_e32 v39, 0, v39, vcc
	v_cmp_lt_f32_e32 vcc, s29, v42
	v_add_f32_e32 v38, v39, v38
	s_nop 0
	v_cndmask_b32_e32 v39, 0, v40, vcc
	v_add_f32_e32 v38, v39, v38
	v_sub_f32_e32 v39, v45, v34
	v_exp_f32_e32 v39, v39
	v_sub_f32_e32 v40, v44, v34
	v_exp_f32_e32 v40, v40
	v_cmp_lt_f32_e32 vcc, s29, v45
	s_nop 1
	v_cndmask_b32_e32 v39, 0, v39, vcc
	v_cmp_lt_f32_e32 vcc, s29, v44
	v_add_f32_e32 v38, v39, v38
	s_nop 0
	v_cndmask_b32_e32 v39, 0, v40, vcc
	v_add_f32_e32 v38, v39, v38
	v_sub_f32_e32 v39, v36, v34
	v_exp_f32_e32 v39, v39
	v_sub_f32_e32 v40, v35, v34
	v_exp_f32_e32 v40, v40
	v_cmp_lt_f32_e32 vcc, s29, v36
	s_nop 1
	v_cndmask_b32_e32 v36, 0, v39, vcc
	v_cmp_lt_f32_e32 vcc, s29, v35
	v_add_f32_e32 v36, v36, v38
	s_nop 0
	v_cndmask_b32_e32 v35, 0, v40, vcc
	v_add_f32_e32 v35, v35, v36
	v_add_f32_e32 v35, v37, v35

.LBB0_864:
	s_add_i32 s40, s73, 2
	s_cmp_gt_i32 s40, s66
	s_cselect_b64 s[18:19], -1, 0
	s_add_i32 s74, s40, s65
	s_cmp_eq_u32 s72, s73
	s_cselect_b32 s75, s67, s21
	s_and_b64 s[40:41], s[18:19], exec
	s_cselect_b32 s40, s68, s22
	s_cselect_b32 s74, s75, s74
	v_mov_b32_e32 v0, v165
	s_cselect_b32 s41, s69, s23
	s_add_u32 s40, s40, s3
	s_addc_u32 s41, s41, 0
	v_ashrrev_i32_e32 v34, 3, v0
	s_lshl_b32 s74, s74, 6
	v_add_u32_e32 v34, s74, v34
	s_and_b64 s[18:19], s[18:19], exec
	v_ashrrev_i32_e32 v35, 31, v34
	s_cselect_b32 s18, 10, 9
	v_lshlrev_b64 v[34:35], s18, v[34:35]
	v_lshlrev_b32_e32 v0, 4, v0
	v_lshl_add_u64 v[34:35], v[34:35], 1, s[40:41]
	v_and_b32_e32 v0, 0x70, v0
	v_lshl_add_u64 v[34:35], v[34:35], 0, v[0:1]
	v_mov_b32_e32 v0, v165
	global_load_dwordx4 v[90:93], v[34:35], off
	s_cmp_le_i32 s70, s25
	v_ashrrev_i32_e32 v34, 3, v0
	v_add_u32_e32 v34, s74, v34
	v_ashrrev_i32_e32 v35, 31, v34
	v_lshlrev_b64 v[34:35], s18, v[34:35]
	v_lshlrev_b32_e32 v0, 4, v0
	v_lshl_add_u64 v[34:35], v[34:35], 1, s[40:41]
	v_and_b32_e32 v0, 0x70, v0
	v_lshl_add_u64 v[34:35], v[34:35], 0, v[0:1]
	global_load_dwordx4 v[94:97], v[34:35], off offset:512
	s_cselect_b64 s[18:19], -1, 0
	s_add_i32 s40, s33, s70
	s_addk_i32 s40, 0xedc1
	s_cmpk_gt_i32 s40, 0xfdff
	s_cselect_b64 s[40:41], -1, 0
	s_and_b64 s[18:19], s[18:19], s[40:41]
	s_mul_i32 s40, s64, 0x2400
	v_add_u32_e32 v126, s40, v184
	ds_read_b128 v[110:113], v126
	ds_read_b128 v[106:109], v126 offset:32
	ds_read_b128 v[98:101], v126 offset:64
	ds_read_b128 v[102:105], v126 offset:96
	s_mul_i32 s74, s64, 0x3000
	s_andn2_b64 vcc, exec, s[18:19]
	s_mov_b64 s[18:19], -1
	s_cbranch_vccz .LBB0_868
	s_waitcnt lgkmcnt(3)
	v_mfma_f32_32x32x16_bf16 v[44:59], v[110:113], v[66:69], 0
	v_mov_b32_e32 v0, v123
	ds_read_b128 v[34:37], v126 offset:4608
	ds_read_b128 v[60:63], v126 offset:4640
	ds_read_b128 v[128:131], v126 offset:4672
	ds_read_b128 v[190:193], v126 offset:4704
	s_nop 0
	v_add_u32_e32 v127, -1, v0
	v_cvt_f32_u32_e32 v38, v0
	s_waitcnt lgkmcnt(6)
	v_mfma_f32_32x32x16_bf16 v[44:59], v[106:109], v[70:73], v[44:59]
	v_cvt_f32_u32_e32 v39, v127
	v_add_u32_e32 v132, -3, v0
	v_add_u32_e32 v133, -2, v0
	v_cvt_f32_u32_e32 v41, v132
	v_cvt_f32_u32_e32 v40, v133
	v_add_u32_e32 v135, -5, v0
	v_add_u32_e32 v139, -4, v0
	s_waitcnt lgkmcnt(5)
	v_mfma_f32_32x32x16_bf16 v[44:59], v[98:101], v[74:77], v[44:59]
	v_cvt_f32_u32_e32 v43, v135
	v_cvt_f32_u32_e32 v42, v139
	v_cmp_gt_u32_e32 vcc, s81, v127
	v_add_u32_e32 v127, -7, v0
	v_add_u32_e32 v188, -6, v0
	s_waitcnt lgkmcnt(4)
	v_mfma_f32_32x32x16_bf16 v[44:59], v[102:105], v[78:81], v[44:59]
	s_nop 11
	v_pk_fma_f32 v[38:39], v[118:119], v[38:39], v[44:45] neg_lo:[1,0,0] neg_hi:[1,0,0]
	v_pk_fma_f32 v[40:41], v[118:119], v[40:41], v[46:47] neg_lo:[1,0,0] neg_hi:[1,0,0]
	v_cndmask_b32_e32 v137, v144, v39, vcc
	v_cmp_gt_u32_e32 vcc, s81, v0
	v_pk_fma_f32 v[64:65], v[118:119], v[42:43], v[48:49] neg_lo:[1,0,0] neg_hi:[1,0,0]
	s_nop 0
	v_cndmask_b32_e32 v138, v144, v38, vcc
	v_cmp_gt_u32_e32 vcc, s81, v132
	v_max3_f32 v38, v138, s28, v137
	v_cvt_f32_u32_e32 v132, v188
	v_cndmask_b32_e32 v134, v144, v41, vcc
	v_cmp_gt_u32_e32 vcc, s81, v133
	v_cvt_f32_u32_e32 v133, v127
	v_pk_fma_f32 v[50:51], v[118:119], v[132:133], v[50:51] neg_lo:[1,0,0] neg_hi:[1,0,0]
	v_cndmask_b32_e32 v136, v144, v40, vcc
	v_cmp_gt_u32_e32 vcc, s81, v135
	s_nop 1
	v_cndmask_b32_e32 v135, v144, v65, vcc
	v_max3_f32 v65, v38, v136, v134
	s_waitcnt lgkmcnt(3)
	v_mfma_f32_32x32x16_bf16 v[34:49], v[34:37], v[66:69], 0
	v_cmp_gt_u32_e32 vcc, s81, v139
	s_nop 1
	v_cndmask_b32_e32 v187, v144, v64, vcc
	v_cmp_gt_u32_e32 vcc, s81, v127
	v_max3_f32 v64, v65, v187, v135
	v_mov_b32_e32 v127, v124
	s_waitcnt lgkmcnt(2)
	v_mfma_f32_32x32x16_bf16 v[34:49], v[60:63], v[70:73], v[34:49]
	v_add_u32_e32 v62, -16, v0
	v_subrev_u32_e32 v63, 17, v0
	v_cvt_f32_u32_e32 v60, v62
	v_cvt_f32_u32_e32 v61, v63
	v_cndmask_b32_e32 v186, v144, v51, vcc
	v_cmp_gt_u32_e32 vcc, s81, v188
	s_waitcnt lgkmcnt(1)
	v_mfma_f32_32x32x16_bf16 v[34:49], v[128:131], v[74:77], v[34:49]
	v_cndmask_b32_e32 v189, v144, v50, vcc
	v_fma_f32 v50, -v118, v60, v52
	v_fma_f32 v51, -v119, v61, v53
	v_subrev_u32_e32 v60, 19, v0
	v_subrev_u32_e32 v61, 18, v0
	v_cvt_f32_u32_e32 v53, v60
	v_cvt_f32_u32_e32 v52, v61
	v_cmp_gt_u32_e32 vcc, s81, v63
	s_waitcnt lgkmcnt(0)
	v_mfma_f32_32x32x16_bf16 v[34:49], v[190:193], v[78:81], v[34:49]
	v_max3_f32 v64, v64, v189, v186
	v_cndmask_b32_e32 v188, v144, v51, vcc
	v_cmp_gt_u32_e32 vcc, s81, v62
	s_nop 1
	v_cndmask_b32_e32 v191, v144, v50, vcc
	v_fma_f32 v50, -v118, v52, v54
	v_fma_f32 v51, -v119, v53, v55
	v_subrev_u32_e32 v54, 21, v0
	v_subrev_u32_e32 v55, 20, v0
	v_cvt_f32_u32_e32 v53, v54
	v_cvt_f32_u32_e32 v52, v55
	v_cmp_gt_u32_e32 vcc, s81, v60
	v_max3_f32 v62, v64, v191, v188
	s_nop 0
	v_cndmask_b32_e32 v190, v144, v51, vcc
	v_cmp_gt_u32_e32 vcc, s81, v61
	s_nop 1
	v_cndmask_b32_e32 v193, v144, v50, vcc
	v_pk_fma_f32 v[50:51], v[118:119], v[52:53], v[56:57] neg_lo:[1,0,0] neg_hi:[1,0,0]
	v_cmp_gt_u32_e32 vcc, s81, v54
	v_subrev_u32_e32 v54, 23, v0
	v_subrev_u32_e32 v56, 22, v0
	v_cvt_f32_u32_e32 v53, v54
	v_cvt_f32_u32_e32 v52, v56
	v_cndmask_b32_e32 v192, v144, v51, vcc
	v_cmp_gt_u32_e32 vcc, s81, v55
	v_max3_f32 v60, v62, v193, v190
	s_nop 0
	v_cndmask_b32_e32 v196, v144, v50, vcc
	v_pk_fma_f32 v[50:51], v[118:119], v[52:53], v[58:59] neg_lo:[1,0,0] neg_hi:[1,0,0]
	v_cmp_gt_u32_e32 vcc, s81, v54
	v_subrev_u32_e32 v54, 32, v0
	v_cvt_f32_u32_e32 v52, v54
	v_cndmask_b32_e32 v194, v144, v51, vcc
	v_subrev_u32_e32 v51, 33, v0
	v_cvt_f32_u32_e32 v53, v51
	v_cmp_gt_u32_e32 vcc, s81, v56
	v_max3_f32 v55, v60, v196, v192
	v_pk_fma_f32 v[34:35], v[118:119], v[52:53], v[34:35] neg_lo:[1,0,0] neg_hi:[1,0,0]
	v_subrev_u32_e32 v52, 35, v0
	v_subrev_u32_e32 v53, 34, v0
	v_cndmask_b32_e32 v198, v144, v50, vcc
	v_cmp_gt_u32_e32 vcc, s81, v51
	v_cvt_f32_u32_e32 v51, v52
	v_cvt_f32_u32_e32 v50, v53
	v_cndmask_b32_e32 v195, v144, v35, vcc
	v_cmp_gt_u32_e32 vcc, s81, v54
	v_max3_f32 v55, v55, v198, v194
	s_nop 0
	v_cndmask_b32_e32 v199, v144, v34, vcc
	v_pk_fma_f32 v[34:35], v[118:119], v[50:51], v[36:37] neg_lo:[1,0,0] neg_hi:[1,0,0]
	v_subrev_u32_e32 v50, 37, v0
	v_subrev_u32_e32 v51, 36, v0
	v_cvt_f32_u32_e32 v37, v50
	v_cvt_f32_u32_e32 v36, v51
	v_cmp_gt_u32_e32 vcc, s81, v52
	v_max3_f32 v54, v55, v199, v195
	s_nop 0
	v_cndmask_b32_e32 v197, v144, v35, vcc
	v_cmp_gt_u32_e32 vcc, s81, v53
	s_nop 1
	v_cndmask_b32_e32 v201, v144, v34, vcc
	v_pk_fma_f32 v[34:35], v[118:119], v[36:37], v[38:39] neg_lo:[1,0,0] neg_hi:[1,0,0]
	v_subrev_u32_e32 v38, 39, v0
	v_subrev_u32_e32 v39, 38, v0
	v_cvt_f32_u32_e32 v37, v38
	v_cvt_f32_u32_e32 v36, v39
	v_cmp_gt_u32_e32 vcc, s81, v50
	v_max3_f32 v52, v54, v201, v197
	s_nop 0
	v_cndmask_b32_e32 v200, v144, v35, vcc
	v_cmp_gt_u32_e32 vcc, s81, v51
	s_nop 1
	v_cndmask_b32_e32 v203, v144, v34, vcc
	v_pk_fma_f32 v[34:35], v[118:119], v[36:37], v[40:41] neg_lo:[1,0,0] neg_hi:[1,0,0]
	v_cmp_gt_u32_e32 vcc, s81, v38
	v_subrev_u32_e32 v38, 49, v0
	v_subrev_u32_e32 v40, 48, v0
	v_cvt_f32_u32_e32 v37, v38
	v_cvt_f32_u32_e32 v36, v40
	v_cndmask_b32_e32 v202, v144, v35, vcc
	v_cmp_gt_u32_e32 vcc, s81, v39
	v_subrev_u32_e32 v41, 50, v0
	v_max3_f32 v50, v52, v203, v200
	v_cndmask_b32_e32 v205, v144, v34, vcc
	v_cmp_gt_u32_e32 vcc, s81, v38
	v_subrev_u32_e32 v38, 51, v0
	v_pk_fma_f32 v[34:35], v[118:119], v[36:37], v[42:43] neg_lo:[1,0,0] neg_hi:[1,0,0]
	v_cvt_f32_u32_e32 v37, v38
	v_cvt_f32_u32_e32 v36, v41
	v_cndmask_b32_e32 v204, v144, v35, vcc
	v_cmp_gt_u32_e32 vcc, s81, v40
	v_subrev_u32_e32 v40, 52, v0
	v_max3_f32 v39, v50, v205, v202
	v_cndmask_b32_e32 v139, v144, v34, vcc
	v_cmp_gt_u32_e32 vcc, s81, v38
	v_subrev_u32_e32 v38, 53, v0
	v_pk_fma_f32 v[34:35], v[118:119], v[36:37], v[44:45] neg_lo:[1,0,0] neg_hi:[1,0,0]
	v_cvt_f32_u32_e32 v37, v38
	v_cvt_f32_u32_e32 v36, v40
	v_cndmask_b32_e32 v132, v144, v35, vcc
	v_cmp_gt_u32_e32 vcc, s81, v41
	v_max3_f32 v39, v39, v139, v204
	s_nop 0
	v_cndmask_b32_e32 v133, v144, v34, vcc
	v_cmp_gt_u32_e32 vcc, s81, v38
	v_subrev_u32_e32 v38, 55, v0
	v_subrev_u32_e32 v0, 54, v0
	v_pk_fma_f32 v[34:35], v[118:119], v[36:37], v[46:47] neg_lo:[1,0,0] neg_hi:[1,0,0]
	v_cvt_f32_u32_e32 v37, v38
	v_cvt_f32_u32_e32 v36, v0
	v_cndmask_b32_e32 v131, v144, v35, vcc
	v_cmp_gt_u32_e32 vcc, s81, v40
	v_max3_f32 v39, v39, v133, v132
	s_nop 0
	v_cndmask_b32_e32 v129, v144, v34, vcc
	v_pk_fma_f32 v[34:35], v[118:119], v[36:37], v[48:49] neg_lo:[1,0,0] neg_hi:[1,0,0]
	v_cmp_gt_u32_e32 vcc, s81, v38
	v_max3_f32 v39, v39, v129, v131
	s_nop 0
	v_cndmask_b32_e32 v130, v144, v35, vcc
	v_cmp_gt_u32_e32 vcc, s81, v0
	v_cndmask_b32_e32 v128, v144, v34, vcc
	v_max3_f32 v0, v39, v128, v130
	s_nop 0
	v_mov_b32_e32 v34, v0
	s_nop 1
	v_permlane32_swap_b32 v34, v0
	s_waitcnt lgkmcnt(0)
	v_max3_f32 v0, v125, v0, v34
	v_cmp_gt_f32_e32 vcc, v0, v125
	s_cbranch_vccz .LBB0_867
	v_sub_f32_e32 v34, v125, v0
	v_exp_f32_e32 v34, v34
	s_nop 0
	v_mul_f32_e32 v127, v124, v34
	v_pk_mul_f32 v[32:33], v[32:33], v[34:35] op_sel_hi:[1,0]
	v_pk_mul_f32 v[30:31], v[30:31], v[34:35] op_sel_hi:[1,0]
	v_pk_mul_f32 v[28:29], v[28:29], v[34:35] op_sel_hi:[1,0]
	v_pk_mul_f32 v[26:27], v[26:27], v[34:35] op_sel_hi:[1,0]
	v_pk_mul_f32 v[24:25], v[24:25], v[34:35] op_sel_hi:[1,0]
	v_pk_mul_f32 v[22:23], v[22:23], v[34:35] op_sel_hi:[1,0]
	v_pk_mul_f32 v[20:21], v[20:21], v[34:35] op_sel_hi:[1,0]
	v_pk_mul_f32 v[18:19], v[18:19], v[34:35] op_sel_hi:[1,0]
	v_pk_mul_f32 v[16:17], v[16:17], v[34:35] op_sel_hi:[1,0]
	v_pk_mul_f32 v[14:15], v[14:15], v[34:35] op_sel_hi:[1,0]
	v_pk_mul_f32 v[12:13], v[12:13], v[34:35] op_sel_hi:[1,0]
	v_pk_mul_f32 v[10:11], v[10:11], v[34:35] op_sel_hi:[1,0]
	v_pk_mul_f32 v[8:9], v[8:9], v[34:35] op_sel_hi:[1,0]
	v_pk_mul_f32 v[6:7], v[6:7], v[34:35] op_sel_hi:[1,0]
	v_pk_mul_f32 v[4:5], v[4:5], v[34:35] op_sel_hi:[1,0]
	v_pk_mul_f32 v[2:3], v[2:3], v[34:35] op_sel_hi:[1,0]

.LBB0_868:
	s_and_b64 vcc, exec, s[18:19]
	s_cbranch_vccz .LBB0_872
	s_waitcnt lgkmcnt(3)
	v_mfma_f32_32x32x16_bf16 v[50:65], v[110:113], v[66:69], 0
	v_mov_b32_e32 v0, v123
	s_waitcnt lgkmcnt(2)
	v_mfma_f32_32x32x16_bf16 v[50:65], v[106:109], v[70:73], v[50:65]
	s_waitcnt lgkmcnt(1)
	v_mfma_f32_32x32x16_bf16 v[50:65], v[98:101], v[74:77], v[50:65]
	ds_read_b128 v[34:37], v126 offset:4608
	ds_read_b128 v[98:101], v126 offset:4640
	s_waitcnt lgkmcnt(1)
	v_mfma_f32_32x32x16_bf16 v[34:49], v[34:37], v[66:69], 0
	s_waitcnt lgkmcnt(0)
	v_mfma_f32_32x32x16_bf16 v[34:49], v[98:101], v[70:73], v[34:49]
	ds_read_b128 v[98:101], v126 offset:4672
	s_waitcnt lgkmcnt(0)
	v_mfma_f32_32x32x16_bf16 v[34:49], v[98:101], v[74:77], v[34:49]
	ds_read_b128 v[98:101], v126 offset:4704
	s_nop 0
	v_cvt_f32_i32_e32 v110, v0
	v_mfma_f32_32x32x16_bf16 v[50:65], v[102:105], v[78:81], v[50:65]
	s_waitcnt lgkmcnt(0)
	v_mfma_f32_32x32x16_bf16 v[34:49], v[98:101], v[78:81], v[34:49]
	s_nop 9
	v_add_f32_e32 v109, v148, v50
	v_add_f32_e32 v108, v118, v51
	v_max3_f32 v0, v109, s28, v108
	v_add_f32_e32 v107, v149, v52
	v_add_f32_e32 v106, v150, v53
	v_max3_f32 v0, v0, v107, v106
	v_add_f32_e32 v105, v151, v54
	v_add_f32_e32 v104, v152, v55
	v_max3_f32 v0, v0, v105, v104
	v_add_f32_e32 v103, v153, v56
	v_add_f32_e32 v102, v154, v57
	v_max3_f32 v0, v0, v103, v102
	v_add_f32_e32 v101, v155, v58
	v_add_f32_e32 v100, v156, v59
	v_max3_f32 v0, v0, v101, v100
	v_add_f32_e32 v99, v157, v60
	v_add_f32_e32 v98, v158, v61
	v_max3_f32 v0, v0, v99, v98
	v_add_f32_e32 v61, v159, v62
	v_add_f32_e32 v60, v160, v63
	v_max3_f32 v0, v0, v61, v60
	v_add_f32_e32 v59, v161, v64
	v_add_f32_e32 v58, v162, v65
	v_max3_f32 v0, v0, v59, v58
	v_add_f32_e32 v57, v163, v34
	v_add_f32_e32 v56, v166, v35
	v_max3_f32 v0, v0, v57, v56
	v_add_f32_e32 v55, v167, v36
	v_add_f32_e32 v54, v168, v37
	v_max3_f32 v0, v0, v55, v54
	v_add_f32_e32 v53, v169, v38
	v_add_f32_e32 v52, v170, v39
	v_max3_f32 v0, v0, v53, v52
	v_add_f32_e32 v51, v171, v40
	v_add_f32_e32 v50, v172, v41
	v_max3_f32 v0, v0, v51, v50
	v_add_f32_e32 v41, v173, v42
	v_add_f32_e32 v40, v174, v43
	v_max3_f32 v0, v0, v41, v40
	v_add_f32_e32 v39, v175, v44
	v_add_f32_e32 v38, v176, v45
	v_max3_f32 v0, v0, v39, v38
	v_add_f32_e32 v37, v177, v46
	v_add_f32_e32 v36, v178, v47
	v_max3_f32 v0, v0, v37, v36
	v_add_f32_e32 v35, v179, v48
	v_add_f32_e32 v34, v180, v49
	v_max3_f32 v0, v0, v35, v34
	v_fma_f32 v0, -v118, v110, v0
	v_mov_b32_e32 v42, v0
	s_nop 1
	v_permlane32_swap_b32 v42, v0
	s_waitcnt lgkmcnt(0)
	v_max3_f32 v0, v125, v0, v42
	v_cmp_gt_f32_e32 vcc, v0, v125
	s_cbranch_vccz .LBB0_871
	v_sub_f32_e32 v42, v125, v0
	v_exp_f32_e32 v42, v42
	s_nop 0
	v_mul_f32_e32 v124, v124, v42
	v_pk_mul_f32 v[32:33], v[32:33], v[42:43] op_sel_hi:[1,0]
	v_pk_mul_f32 v[30:31], v[30:31], v[42:43] op_sel_hi:[1,0]
	v_pk_mul_f32 v[28:29], v[28:29], v[42:43] op_sel_hi:[1,0]
	v_pk_mul_f32 v[26:27], v[26:27], v[42:43] op_sel_hi:[1,0]
	v_pk_mul_f32 v[24:25], v[24:25], v[42:43] op_sel_hi:[1,0]
	v_pk_mul_f32 v[22:23], v[22:23], v[42:43] op_sel_hi:[1,0]
	v_pk_mul_f32 v[20:21], v[20:21], v[42:43] op_sel_hi:[1,0]
	v_pk_mul_f32 v[18:19], v[18:19], v[42:43] op_sel_hi:[1,0]
	v_pk_mul_f32 v[16:17], v[16:17], v[42:43] op_sel_hi:[1,0]
	v_pk_mul_f32 v[14:15], v[14:15], v[42:43] op_sel_hi:[1,0]
	v_pk_mul_f32 v[12:13], v[12:13], v[42:43] op_sel_hi:[1,0]
	v_pk_mul_f32 v[10:11], v[10:11], v[42:43] op_sel_hi:[1,0]
	v_pk_mul_f32 v[8:9], v[8:9], v[42:43] op_sel_hi:[1,0]
	v_pk_mul_f32 v[6:7], v[6:7], v[42:43] op_sel_hi:[1,0]
	v_pk_mul_f32 v[4:5], v[4:5], v[42:43] op_sel_hi:[1,0]
	v_pk_mul_f32 v[2:3], v[2:3], v[42:43] op_sel_hi:[1,0]

.LBB0_878:
	v_mov_b32_e32 v0, v165
	s_lshl_b32 s2, s30, 6
	v_ashrrev_i32_e32 v34, 3, v0
	v_add_u32_e32 v34, s2, v34
	v_ashrrev_i32_e32 v35, 31, v34
	v_lshlrev_b64 v[34:35], 11, v[34:35]
	v_lshlrev_b32_e32 v0, 4, v0
	v_lshl_add_u64 v[34:35], s[14:15], 0, v[34:35]
	v_and_b32_e32 v0, 0x70, v0
	v_lshl_add_u64 v[34:35], v[34:35], 0, v[0:1]
	v_mov_b32_e32 v0, v165
	global_load_dwordx4 v[90:93], v[34:35], off
	s_nop 0
	v_ashrrev_i32_e32 v34, 3, v0
	v_add_u32_e32 v34, s2, v34
	v_ashrrev_i32_e32 v35, 31, v34
	v_lshlrev_b64 v[34:35], 11, v[34:35]
	v_lshlrev_b32_e32 v0, 4, v0
	v_lshl_add_u64 v[34:35], s[16:17], 0, v[34:35]
	v_and_b32_e32 v0, 0x70, v0
	v_lshl_add_u64 v[34:35], v[34:35], 0, v[0:1]
	global_load_dwordx4 v[94:97], v[34:35], off
	s_ashr_i32 s2, s67, 6
	v_lshl_add_u32 v0, s2, 3, v185
	ds_read_b64 v[34:35], v0 offset:59904
	s_waitcnt lgkmcnt(0)
	v_lshrrev_b64 v[34:35], s67, v[34:35]
	v_and_b32_e32 v0, 1, v34
	v_cmp_eq_u32_e64 s[10:11], 1, v0
	v_cmp_ne_u32_e32 vcc, 0, v0
	s_cbranch_vccz .LBB0_888
	s_lshl_b32 s3, s67, 6
	s_or_b32 s2, s3, 63
	s_cmp_gt_i32 s2, s25
	s_mul_i32 s2, s64, 0x2400
	v_add_u32_e32 v192, s2, v184
	ds_read_b128 v[98:101], v192
	ds_read_b128 v[102:105], v192 offset:32
	ds_read_b128 v[106:109], v192 offset:64
	ds_read_b128 v[110:113], v192 offset:96
	v_add_u32_e32 v0, s3, v120
	s_mul_i32 s2, s64, 0x3000
	s_mov_b64 s[18:19], -1
	v_sub_u32_e32 v190, v187, v0
	s_cbranch_scc1 .LBB0_883
	s_waitcnt lgkmcnt(3)
	v_mfma_f32_32x32x16_bf16 v[50:65], v[98:101], v[66:69], 0
	ds_read_b128 v[34:37], v192 offset:4608
	ds_read_b128 v[194:197], v192 offset:4640
	v_mov_b32_e32 v0, v190
	v_mov_b32_e32 v201, v188
	s_waitcnt lgkmcnt(1)
	v_mfma_f32_32x32x16_bf16 v[34:49], v[34:37], v[66:69], 0
	v_mfma_f32_32x32x16_bf16 v[50:65], v[102:105], v[70:73], v[50:65]
	s_waitcnt lgkmcnt(0)
	v_mfma_f32_32x32x16_bf16 v[34:49], v[194:197], v[70:73], v[34:49]
	ds_read_b128 v[194:197], v192 offset:4672
	v_mfma_f32_32x32x16_bf16 v[50:65], v[106:109], v[74:77], v[50:65]
	s_waitcnt lgkmcnt(0)
	v_mfma_f32_32x32x16_bf16 v[34:49], v[194:197], v[74:77], v[34:49]
	ds_read_b128 v[194:197], v192 offset:4704
	s_nop 0
	v_cvt_f32_i32_e32 v225, v0
	v_mfma_f32_32x32x16_bf16 v[50:65], v[110:113], v[78:81], v[50:65]
	s_waitcnt lgkmcnt(0)
	v_mfma_f32_32x32x16_bf16 v[34:49], v[194:197], v[78:81], v[34:49]
	s_nop 9
	v_add_f32_e32 v224, v148, v50
	v_add_f32_e32 v223, v118, v51
	v_max3_f32 v0, v224, s28, v223
	v_add_f32_e32 v222, v149, v52
	v_add_f32_e32 v221, v150, v53
	v_max3_f32 v0, v0, v222, v221
	v_add_f32_e32 v220, v151, v54
	v_add_f32_e32 v219, v152, v55
	v_max3_f32 v0, v0, v220, v219
	v_add_f32_e32 v218, v153, v56
	v_add_f32_e32 v217, v154, v57
	v_max3_f32 v0, v0, v218, v217
	v_add_f32_e32 v216, v155, v58
	v_add_f32_e32 v215, v156, v59
	v_max3_f32 v0, v0, v216, v215
	v_add_f32_e32 v214, v157, v60
	v_add_f32_e32 v213, v158, v61
	v_max3_f32 v0, v0, v214, v213
	v_add_f32_e32 v212, v159, v62
	v_add_f32_e32 v211, v160, v63
	v_max3_f32 v0, v0, v212, v211
	v_add_f32_e32 v210, v161, v64
	v_add_f32_e32 v209, v162, v65
	v_max3_f32 v0, v0, v210, v209
	v_add_f32_e32 v208, v163, v34
	v_add_f32_e32 v207, v166, v35
	v_max3_f32 v0, v0, v208, v207
	v_add_f32_e32 v206, v167, v36
	v_add_f32_e32 v205, v168, v37
	v_max3_f32 v0, v0, v206, v205
	v_add_f32_e32 v204, v169, v38
	v_add_f32_e32 v203, v170, v39
	v_max3_f32 v0, v0, v204, v203
	v_add_f32_e32 v202, v171, v40
	v_add_f32_e32 v200, v172, v41
	v_max3_f32 v0, v0, v202, v200
	v_add_f32_e32 v199, v173, v42
	v_add_f32_e32 v198, v174, v43
	v_max3_f32 v0, v0, v199, v198
	v_add_f32_e32 v197, v175, v44
	v_add_f32_e32 v196, v176, v45
	v_max3_f32 v0, v0, v197, v196
	v_add_f32_e32 v195, v177, v46
	v_add_f32_e32 v194, v178, v47
	v_max3_f32 v0, v0, v195, v194
	v_add_f32_e32 v193, v179, v48
	v_add_f32_e32 v191, v180, v49
	v_max3_f32 v0, v0, v193, v191
	v_fma_f32 v0, -v118, v225, v0
	v_cndmask_b32_e64 v0, v144, v0, s[10:11]
	v_mov_b32_e32 v34, v0
	s_nop 1
	v_permlane32_swap_b32 v34, v0
	s_waitcnt lgkmcnt(0)
	v_max3_f32 v0, v189, v0, v34
	v_cmp_gt_f32_e32 vcc, v0, v189
	s_cbranch_vccz .LBB0_882
	v_sub_f32_e32 v34, v189, v0
	v_exp_f32_e32 v34, v34
	s_nop 0
	v_mul_f32_e32 v201, v188, v34
	v_pk_mul_f32 v[32:33], v[32:33], v[34:35] op_sel_hi:[1,0]
	v_pk_mul_f32 v[30:31], v[30:31], v[34:35] op_sel_hi:[1,0]
	v_pk_mul_f32 v[28:29], v[28:29], v[34:35] op_sel_hi:[1,0]
	v_pk_mul_f32 v[26:27], v[26:27], v[34:35] op_sel_hi:[1,0]
	v_pk_mul_f32 v[24:25], v[24:25], v[34:35] op_sel_hi:[1,0]
	v_pk_mul_f32 v[22:23], v[22:23], v[34:35] op_sel_hi:[1,0]
	v_pk_mul_f32 v[20:21], v[20:21], v[34:35] op_sel_hi:[1,0]
	v_pk_mul_f32 v[18:19], v[18:19], v[34:35] op_sel_hi:[1,0]
	v_pk_mul_f32 v[16:17], v[16:17], v[34:35] op_sel_hi:[1,0]
	v_pk_mul_f32 v[14:15], v[14:15], v[34:35] op_sel_hi:[1,0]
	v_pk_mul_f32 v[12:13], v[12:13], v[34:35] op_sel_hi:[1,0]
	v_pk_mul_f32 v[10:11], v[10:11], v[34:35] op_sel_hi:[1,0]
	v_pk_mul_f32 v[8:9], v[8:9], v[34:35] op_sel_hi:[1,0]
	v_pk_mul_f32 v[6:7], v[6:7], v[34:35] op_sel_hi:[1,0]
	v_pk_mul_f32 v[4:5], v[4:5], v[34:35] op_sel_hi:[1,0]
	v_pk_mul_f32 v[2:3], v[2:3], v[34:35] op_sel_hi:[1,0]

.LBB0_883:
	s_waitcnt lgkmcnt(3)
	v_mfma_f32_32x32x16_bf16 v[50:65], v[98:101], v[66:69], 0
	s_nop 3
	ds_read_b128 v[34:37], v192 offset:4608
	ds_read_b128 v[98:101], v192 offset:4640
	s_waitcnt lgkmcnt(1)
	v_mfma_f32_32x32x16_bf16 v[34:49], v[34:37], v[66:69], 0
	v_mfma_f32_32x32x16_bf16 v[50:65], v[102:105], v[70:73], v[50:65]
	s_waitcnt lgkmcnt(0)
	v_mfma_f32_32x32x16_bf16 v[34:49], v[98:101], v[70:73], v[34:49]
	ds_read_b128 v[98:101], v192 offset:4672
	v_mfma_f32_32x32x16_bf16 v[50:65], v[106:109], v[74:77], v[50:65]
	v_mfma_f32_32x32x16_bf16 v[50:65], v[110:113], v[78:81], v[50:65]
	s_waitcnt lgkmcnt(0)
	v_mfma_f32_32x32x16_bf16 v[34:49], v[98:101], v[74:77], v[34:49]
	ds_read_b128 v[98:101], v192 offset:4704
	s_nop 0
	v_cvt_f32_u32_e32 v0, v190
	v_cmp_gt_u32_e32 vcc, s88, v190
	s_and_b64 vcc, s[10:11], vcc
	s_nop 4
	v_fma_f32 v0, -v118, v0, v50
	s_waitcnt lgkmcnt(0)
	v_mfma_f32_32x32x16_bf16 v[34:49], v[98:101], v[78:81], v[34:49]
	v_cndmask_b32_e32 v98, v144, v0, vcc
	v_add_u32_e32 v0, -1, v190
	v_cvt_f32_u32_e32 v0, v0
	v_cmp_lt_i32_e32 vcc, 0, v190
	s_and_b64 vcc, s[10:11], vcc
	v_fma_f32 v0, -v118, v0, v51
	v_add_u32_e32 v51, -2, v190
	v_cndmask_b32_e32 v50, v144, v0, vcc
	v_cmp_gt_u32_e32 vcc, s88, v51
	v_cvt_f32_u32_e32 v51, v51
	s_and_b64 vcc, s[10:11], vcc
	v_max3_f32 v0, v98, s28, v50
	v_fma_f32 v51, -v118, v51, v52
	v_cndmask_b32_e32 v52, v144, v51, vcc
	v_add_u32_e32 v51, -3, v190
	v_cmp_gt_u32_e32 vcc, s88, v51
	v_cvt_f32_u32_e32 v51, v51
	s_and_b64 vcc, s[10:11], vcc
	v_fma_f32 v51, -v118, v51, v53
	v_add_u32_e32 v53, -4, v190
	v_cndmask_b32_e32 v51, v144, v51, vcc
	v_cmp_gt_u32_e32 vcc, s88, v53
	v_cvt_f32_u32_e32 v53, v53
	s_and_b64 vcc, s[10:11], vcc
	v_max3_f32 v0, v0, v52, v51
	v_fma_f32 v53, -v118, v53, v54
	v_add_u32_e32 v54, -5, v190
	v_cndmask_b32_e32 v53, v144, v53, vcc
	v_cmp_gt_u32_e32 vcc, s88, v54
	v_cvt_f32_u32_e32 v54, v54
	s_and_b64 vcc, s[10:11], vcc
	v_fma_f32 v54, -v118, v54, v55
	v_add_u32_e32 v55, -6, v190
	v_cndmask_b32_e32 v54, v144, v54, vcc
	v_cmp_gt_u32_e32 vcc, s88, v55
	v_cvt_f32_u32_e32 v55, v55
	s_and_b64 vcc, s[10:11], vcc
	v_max3_f32 v0, v0, v53, v54
	v_fma_f32 v55, -v118, v55, v56
	v_add_u32_e32 v56, -7, v190
	v_cndmask_b32_e32 v55, v144, v55, vcc
	v_cmp_gt_u32_e32 vcc, s88, v56
	v_cvt_f32_u32_e32 v56, v56
	s_and_b64 vcc, s[10:11], vcc
	v_fma_f32 v56, -v118, v56, v57
	v_add_u32_e32 v57, -16, v190
	v_cndmask_b32_e32 v56, v144, v56, vcc
	v_cmp_gt_u32_e32 vcc, s88, v57
	v_cvt_f32_u32_e32 v57, v57
	s_and_b64 vcc, s[10:11], vcc
	v_max3_f32 v0, v0, v55, v56
	v_fma_f32 v57, -v118, v57, v58
	v_subrev_u32_e32 v58, 17, v190
	v_cndmask_b32_e32 v57, v144, v57, vcc
	v_cmp_gt_u32_e32 vcc, s88, v58
	v_cvt_f32_u32_e32 v58, v58
	s_and_b64 vcc, s[10:11], vcc
	v_fma_f32 v58, -v118, v58, v59
	v_subrev_u32_e32 v59, 18, v190
	v_cndmask_b32_e32 v58, v144, v58, vcc
	v_cmp_gt_u32_e32 vcc, s88, v59
	v_cvt_f32_u32_e32 v59, v59
	s_and_b64 vcc, s[10:11], vcc
	v_max3_f32 v0, v0, v57, v58
	v_fma_f32 v59, -v118, v59, v60
	v_subrev_u32_e32 v60, 19, v190
	v_cndmask_b32_e32 v59, v144, v59, vcc
	v_cmp_gt_u32_e32 vcc, s88, v60
	v_cvt_f32_u32_e32 v60, v60
	s_and_b64 vcc, s[10:11], vcc
	v_fma_f32 v60, -v118, v60, v61
	v_subrev_u32_e32 v61, 20, v190
	v_cndmask_b32_e32 v60, v144, v60, vcc
	v_cmp_gt_u32_e32 vcc, s88, v61
	v_cvt_f32_u32_e32 v61, v61
	s_and_b64 vcc, s[10:11], vcc
	v_max3_f32 v0, v0, v59, v60
	v_fma_f32 v61, -v118, v61, v62
	v_subrev_u32_e32 v62, 21, v190
	v_cndmask_b32_e32 v61, v144, v61, vcc
	v_cmp_gt_u32_e32 vcc, s88, v62
	v_cvt_f32_u32_e32 v62, v62
	s_and_b64 vcc, s[10:11], vcc
	v_fma_f32 v62, -v118, v62, v63
	v_subrev_u32_e32 v63, 22, v190
	v_cndmask_b32_e32 v62, v144, v62, vcc
	v_cmp_gt_u32_e32 vcc, s88, v63
	v_cvt_f32_u32_e32 v63, v63
	s_and_b64 vcc, s[10:11], vcc
	v_max3_f32 v0, v0, v61, v62
	v_fma_f32 v63, -v118, v63, v64
	v_subrev_u32_e32 v64, 23, v190
	v_cndmask_b32_e32 v63, v144, v63, vcc
	v_cmp_gt_u32_e32 vcc, s88, v64
	v_cvt_f32_u32_e32 v64, v64
	s_and_b64 vcc, s[10:11], vcc
	v_fma_f32 v64, -v118, v64, v65
	v_subrev_u32_e32 v65, 32, v190
	v_cndmask_b32_e32 v64, v144, v64, vcc
	v_cmp_gt_u32_e32 vcc, s88, v65
	v_cvt_f32_u32_e32 v65, v65
	s_and_b64 vcc, s[10:11], vcc
	v_max3_f32 v0, v0, v63, v64
	v_fma_f32 v34, -v118, v65, v34
	v_subrev_u32_e32 v65, 33, v190
	v_cndmask_b32_e32 v34, v144, v34, vcc
	v_cmp_gt_u32_e32 vcc, s88, v65
	v_cvt_f32_u32_e32 v65, v65
	s_and_b64 vcc, s[10:11], vcc
	v_fma_f32 v35, -v118, v65, v35
	v_subrev_u32_e32 v65, 34, v190
	v_cndmask_b32_e32 v35, v144, v35, vcc
	v_cmp_gt_u32_e32 vcc, s88, v65
	v_cvt_f32_u32_e32 v65, v65
	s_and_b64 vcc, s[10:11], vcc
	v_max3_f32 v0, v0, v34, v35
	v_fma_f32 v36, -v118, v65, v36
	v_subrev_u32_e32 v65, 35, v190
	v_cndmask_b32_e32 v36, v144, v36, vcc
	v_cmp_gt_u32_e32 vcc, s88, v65
	v_cvt_f32_u32_e32 v65, v65
	s_and_b64 vcc, s[10:11], vcc
	v_fma_f32 v37, -v118, v65, v37
	v_subrev_u32_e32 v65, 36, v190
	v_cndmask_b32_e32 v37, v144, v37, vcc
	v_cmp_gt_u32_e32 vcc, s88, v65
	v_cvt_f32_u32_e32 v65, v65
	s_and_b64 vcc, s[10:11], vcc
	v_max3_f32 v0, v0, v36, v37
	v_fma_f32 v38, -v118, v65, v38
	v_subrev_u32_e32 v65, 37, v190
	v_cndmask_b32_e32 v38, v144, v38, vcc
	v_cmp_gt_u32_e32 vcc, s88, v65
	v_cvt_f32_u32_e32 v65, v65
	s_and_b64 vcc, s[10:11], vcc
	v_fma_f32 v39, -v118, v65, v39
	v_subrev_u32_e32 v65, 38, v190
	v_cndmask_b32_e32 v39, v144, v39, vcc
	v_cmp_gt_u32_e32 vcc, s88, v65
	v_cvt_f32_u32_e32 v65, v65
	s_and_b64 vcc, s[10:11], vcc
	v_max3_f32 v0, v0, v38, v39
	v_fma_f32 v40, -v118, v65, v40
	v_subrev_u32_e32 v65, 39, v190
	v_cndmask_b32_e32 v40, v144, v40, vcc
	v_cmp_gt_u32_e32 vcc, s88, v65
	v_cvt_f32_u32_e32 v65, v65
	s_and_b64 vcc, s[10:11], vcc
	v_fma_f32 v41, -v118, v65, v41
	v_subrev_u32_e32 v65, 48, v190
	v_cndmask_b32_e32 v41, v144, v41, vcc
	v_cmp_gt_u32_e32 vcc, s88, v65
	v_cvt_f32_u32_e32 v65, v65
	s_and_b64 vcc, s[10:11], vcc
	v_max3_f32 v0, v0, v40, v41
	v_fma_f32 v42, -v118, v65, v42
	v_subrev_u32_e32 v65, 49, v190
	v_cndmask_b32_e32 v42, v144, v42, vcc
	v_cmp_gt_u32_e32 vcc, s88, v65
	v_cvt_f32_u32_e32 v65, v65
	s_and_b64 vcc, s[10:11], vcc
	v_fma_f32 v43, -v118, v65, v43
	v_subrev_u32_e32 v65, 50, v190
	v_cndmask_b32_e32 v43, v144, v43, vcc
	v_cmp_gt_u32_e32 vcc, s88, v65
	v_cvt_f32_u32_e32 v65, v65
	s_and_b64 vcc, s[10:11], vcc
	v_max3_f32 v0, v0, v42, v43
	v_fma_f32 v44, -v118, v65, v44
	v_subrev_u32_e32 v65, 51, v190
	v_cndmask_b32_e32 v44, v144, v44, vcc
	v_cmp_gt_u32_e32 vcc, s88, v65
	v_cvt_f32_u32_e32 v65, v65
	s_and_b64 vcc, s[10:11], vcc
	v_fma_f32 v45, -v118, v65, v45
	v_subrev_u32_e32 v65, 52, v190
	v_cndmask_b32_e32 v45, v144, v45, vcc
	v_cmp_gt_u32_e32 vcc, s88, v65
	v_cvt_f32_u32_e32 v65, v65
	s_and_b64 vcc, s[10:11], vcc
	v_max3_f32 v0, v0, v44, v45
	v_fma_f32 v46, -v118, v65, v46
	v_subrev_u32_e32 v65, 53, v190
	v_cndmask_b32_e32 v46, v144, v46, vcc
	v_cmp_gt_u32_e32 vcc, s88, v65
	v_cvt_f32_u32_e32 v65, v65
	s_and_b64 vcc, s[10:11], vcc
	v_fma_f32 v47, -v118, v65, v47
	v_subrev_u32_e32 v65, 54, v190
	v_cndmask_b32_e32 v47, v144, v47, vcc
	v_cmp_gt_u32_e32 vcc, s88, v65
	v_cvt_f32_u32_e32 v65, v65
	s_and_b64 vcc, s[10:11], vcc
	v_max3_f32 v0, v0, v46, v47
	v_fma_f32 v48, -v118, v65, v48
	v_cndmask_b32_e32 v65, v144, v48, vcc
	v_subrev_u32_e32 v48, 55, v190
	v_cmp_gt_u32_e32 vcc, s88, v48
	v_cvt_f32_u32_e32 v48, v48
	s_and_b64 vcc, s[10:11], vcc
	v_fma_f32 v48, -v118, v48, v49
	v_cndmask_b32_e32 v99, v144, v48, vcc
	v_max3_f32 v0, v0, v65, v99
	v_mov_b32_e32 v48, v0
	s_nop 1
	v_permlane32_swap_b32 v48, v0
	s_waitcnt lgkmcnt(0)
	v_max3_f32 v0, v189, v0, v48
	v_cmp_gt_f32_e32 vcc, v0, v189
	s_cbranch_vccz .LBB0_886
	v_sub_f32_e32 v48, v189, v0
	v_exp_f32_e32 v48, v48
	s_nop 0
	v_mul_f32_e32 v188, v188, v48
	v_pk_mul_f32 v[32:33], v[32:33], v[48:49] op_sel_hi:[1,0]
	v_pk_mul_f32 v[30:31], v[30:31], v[48:49] op_sel_hi:[1,0]
	v_pk_mul_f32 v[28:29], v[28:29], v[48:49] op_sel_hi:[1,0]
	v_pk_mul_f32 v[26:27], v[26:27], v[48:49] op_sel_hi:[1,0]
	v_pk_mul_f32 v[24:25], v[24:25], v[48:49] op_sel_hi:[1,0]
	v_pk_mul_f32 v[22:23], v[22:23], v[48:49] op_sel_hi:[1,0]
	v_pk_mul_f32 v[20:21], v[20:21], v[48:49] op_sel_hi:[1,0]
	v_pk_mul_f32 v[18:19], v[18:19], v[48:49] op_sel_hi:[1,0]
	v_pk_mul_f32 v[16:17], v[16:17], v[48:49] op_sel_hi:[1,0]
	v_pk_mul_f32 v[14:15], v[14:15], v[48:49] op_sel_hi:[1,0]
	v_pk_mul_f32 v[12:13], v[12:13], v[48:49] op_sel_hi:[1,0]
	v_pk_mul_f32 v[10:11], v[10:11], v[48:49] op_sel_hi:[1,0]
	v_pk_mul_f32 v[8:9], v[8:9], v[48:49] op_sel_hi:[1,0]
	v_pk_mul_f32 v[6:7], v[6:7], v[48:49] op_sel_hi:[1,0]
	v_pk_mul_f32 v[4:5], v[4:5], v[48:49] op_sel_hi:[1,0]
	v_pk_mul_f32 v[2:3], v[2:3], v[48:49] op_sel_hi:[1,0]
